# v14 + grid barrier: non-leader workgroups poll the global generation word directly (one polling hop less per barrier)
# baseline (speedup 1.0000x reference)
.LBB0_1060:
	s_or_b64 exec, exec, s[10:11]
	v_cvt_f32_u32_e32 v8, v6
	s_waitcnt vmcnt(0)
	v_readfirstlane_b32 s0, v7
	v_sub_u32_e32 v7, 0, v6
	v_rcp_iflag_f32_e32 v8, v8
	v_add_u32_e32 v9, s0, v5
	v_mul_f32_e32 v8, 0x4f7ffffe, v8
	v_cvt_u32_f32_e32 v8, v8
	v_mul_lo_u32 v5, v7, v8
	v_mul_hi_u32 v5, v8, v5
	v_add_u32_e32 v5, v8, v5
	v_mul_hi_u32 v5, v9, v5
	v_mul_lo_u32 v7, v5, v6
	v_sub_u32_e32 v7, v9, v7
	v_add_u32_e32 v8, 1, v5
	v_cmp_ge_u32_e32 vcc, v7, v6
	s_nop 1
	v_cndmask_b32_e32 v5, v5, v8, vcc
	v_sub_u32_e32 v8, v7, v6
	v_cndmask_b32_e32 v7, v7, v8, vcc
	v_add_u32_e32 v8, 1, v5
	v_cmp_ge_u32_e32 vcc, v7, v6
	v_add_u32_e32 v7, 1, v9
	s_nop 0
	v_cndmask_b32_e32 v5, v5, v8, vcc
	v_mul_lo_u32 v8, v6, v5
	v_add_u32_e32 v6, v8, v6
	v_cmp_ne_u32_e32 vcc, v7, v6
	s_and_saveexec_b64 s[0:1], vcc
	s_xor_b64 s[10:11], exec, s[0:1]
	s_cbranch_execz .LBB0_1074
	s_waitcnt lgkmcnt(0)
	s_add_u32 s16, s78, 0x1f888500
	s_addc_u32 s17, s79, 0
	global_load_dword v4, v181, s[16:17] sc1
	s_waitcnt vmcnt(0)
	v_cmp_eq_u32_e32 vcc, v4, v5
	s_and_saveexec_b64 s[12:13], vcc
	s_cbranch_execz .LBB0_1073
	s_add_u32 s14, s78, 0x1f885200
	s_addc_u32 s15, s79, 0
	s_mov_b32 s0, 1
	s_mov_b64 s[18:19], 0
	s_branch .LBB0_1064
